# attention row-max chain: removed the two redundant self-max canonicalisations after each permlane32_swap (3 sites), on top of the static priority raise
# speedup vs baseline: 1.0048x; 1.0048x over previous
.Lattn_prio_done:
.LBB0_563:
	s_add_i32 s16, s13, -1
	ds_read_b128 v[64:67], v187 offset:57344
	ds_read_b128 v[68:71], v202 offset:57344
	ds_read_b128 v[220:223], v189 offset:57344
	ds_read_b128 v[232:235], v201 offset:57344
	v_add_f32_e32 v178, 0, v136
	v_add_f32_e32 v178, v230, v178
	s_waitcnt lgkmcnt(3)
	v_mfma_f32_32x32x16_bf16 v[80:95], v[64:67], v[96:99], 0
	v_add_f32_e32 v178, v137, v178
	v_add_f32_e32 v178, v229, v178
	v_add_f32_e32 v178, v138, v178
	v_add_f32_e32 v178, v228, v178
	v_add_f32_e32 v178, v139, v178
	v_add_f32_e32 v178, v213, v178
	v_add_f32_e32 v178, v144, v178
	s_waitcnt lgkmcnt(2)
	v_mfma_f32_32x32x16_bf16 v[64:79], v[68:71], v[96:99], 0
	v_add_f32_e32 v178, v147, v178
	v_add_f32_e32 v178, v145, v178
	v_add_f32_e32 v178, v146, v178
	v_exp_f32_e32 v132, v132
	v_add_f32_e32 v178, v141, v178
	v_exp_f32_e32 v133, v133
	v_add_f32_e32 v178, v143, v178
	s_waitcnt lgkmcnt(1)
	v_mfma_f32_32x32x16_bf16 v[80:95], v[220:223], v[100:103], v[80:95]
	v_exp_f32_e32 v134, v134
	v_add_f32_e32 v178, v140, v178
	v_exp_f32_e32 v135, v135
	v_add_f32_e32 v178, v142, v178
	v_exp_f32_e32 v124, v124
	v_add_f32_e32 v178, v132, v178
	v_exp_f32_e32 v125, v125
	s_waitcnt lgkmcnt(0)
	v_mfma_f32_32x32x16_bf16 v[64:79], v[232:235], v[100:103], v[64:79]
	ds_read_b128 v[220:223], v190 offset:57344
	ds_read_b128 v[232:235], v209 offset:57344
	v_add_f32_e32 v178, v133, v178
	v_exp_f32_e32 v126, v126
	v_add_f32_e32 v178, v134, v178
	v_exp_f32_e32 v127, v127
	v_add_f32_e32 v178, v135, v178
	v_exp_f32_e32 v128, v128
	s_waitcnt lgkmcnt(1)
	v_mfma_f32_32x32x16_bf16 v[80:95], v[220:223], v[104:107], v[80:95]
	v_add_f32_e32 v178, v124, v178
	v_exp_f32_e32 v129, v129
	v_add_f32_e32 v178, v125, v178
	v_exp_f32_e32 v130, v130
	v_add_f32_e32 v178, v126, v178
	v_exp_f32_e32 v131, v131
	v_add_f32_e32 v178, v127, v178
	s_waitcnt lgkmcnt(0)
	v_mfma_f32_32x32x16_bf16 v[64:79], v[232:235], v[104:107], v[64:79]
	ds_read_b128 v[220:223], v191 offset:57344
	ds_read_b128 v[232:235], v212 offset:57344
	v_exp_f32_e32 v120, v120
	v_add_f32_e32 v178, v128, v178
	v_exp_f32_e32 v121, v121
	v_add_f32_e32 v178, v129, v178
	v_exp_f32_e32 v122, v122
	v_add_f32_e32 v178, v130, v178
	s_waitcnt lgkmcnt(1)
	v_mfma_f32_32x32x16_bf16 v[80:95], v[220:223], v[108:111], v[80:95]
	v_exp_f32_e32 v123, v123
	v_add_f32_e32 v178, v131, v178
	v_add_f32_e32 v178, v120, v178
	v_add_f32_e32 v178, v121, v178
	v_add_f32_e32 v178, v122, v178
	v_add_f32_e32 v231, v123, v178
	s_waitcnt lgkmcnt(0)
	v_mfma_f32_32x32x16_bf16 v[64:79], v[232:235], v[108:111], v[64:79]
	ds_read_b128 v[220:223], v192 offset:57344
	ds_read_b128 v[232:235], v211 offset:57344
	s_waitcnt lgkmcnt(1)
	v_mfma_f32_32x32x16_bf16 v[80:95], v[220:223], v[112:115], v[80:95]
	s_waitcnt lgkmcnt(0)
	v_mfma_f32_32x32x16_bf16 v[64:79], v[232:235], v[112:115], v[64:79]
	ds_read_b128 v[220:223], v193 offset:57344
	ds_read_b128 v[232:235], v210 offset:57344
	s_waitcnt lgkmcnt(1)
	v_mfma_f32_32x32x16_bf16 v[80:95], v[220:223], v[116:119], v[80:95]
	s_waitcnt lgkmcnt(0)
	v_mfma_f32_32x32x16_bf16 v[64:79], v[232:235], v[116:119], v[64:79]
	ds_read_b128 v[220:223], v194 offset:57344
	ds_read_b128 v[232:235], v208 offset:57344
	ds_read_b128 v[236:239], v171
	s_waitcnt lgkmcnt(0)
	v_mfma_f32_32x32x16_bf16 v[80:95], v[220:223], v[236:239], v[80:95]
	v_mfma_f32_32x32x16_bf16 v[64:79], v[232:235], v[236:239], v[64:79]
	ds_read_b128 v[220:223], v195 offset:57344
	ds_read_b128 v[232:235], v207 offset:57344
	ds_read_b128 v[236:239], v171 offset:1024
	s_waitcnt lgkmcnt(0)
	v_mfma_f32_32x32x16_bf16 v[80:95], v[220:223], v[236:239], v[80:95]
	v_mfma_f32_32x32x16_bf16 v[64:79], v[232:235], v[236:239], v[64:79]
	ds_read_b128 v[220:223], v196 offset:57344
	ds_read_b128 v[232:235], v206 offset:57344
	ds_read_b128 v[236:239], v171 offset:2048
	s_waitcnt lgkmcnt(0)
	v_mfma_f32_32x32x16_bf16 v[80:95], v[220:223], v[236:239], v[80:95]
	v_mfma_f32_32x32x16_bf16 v[64:79], v[232:235], v[236:239], v[64:79]
	ds_read_b128 v[220:223], v197 offset:57344
	ds_read_b128 v[232:235], v205 offset:57344
	ds_read_b128 v[236:239], v171 offset:3072
	s_waitcnt lgkmcnt(0)
	v_mfma_f32_32x32x16_bf16 v[80:95], v[220:223], v[236:239], v[80:95]
	v_mfma_f32_32x32x16_bf16 v[64:79], v[232:235], v[236:239], v[64:79]
	ds_read_b128 v[220:223], v199 offset:57344
	ds_read_b128 v[232:235], v204 offset:57344
	ds_read_b128 v[236:239], v171 offset:4096
	s_waitcnt lgkmcnt(0)
	v_mfma_f32_32x32x16_bf16 v[80:95], v[220:223], v[236:239], v[80:95]
	v_mfma_f32_32x32x16_bf16 v[64:79], v[232:235], v[236:239], v[64:79]
	ds_read_b128 v[220:223], v198 offset:57344
	ds_read_b128 v[232:235], v203 offset:57344
	ds_read_b128 v[236:239], v171 offset:5120
	v_cvt_pk_bf16_f32 v136, v136, v230
	v_cvt_pk_bf16_f32 v137, v137, v229
	v_cvt_pk_bf16_f32 v138, v138, v228
	v_cvt_pk_bf16_f32 v139, v139, v213
	v_cvt_pk_bf16_f32 v144, v144, v147
	v_cvt_pk_bf16_f32 v145, v145, v146
	s_waitcnt lgkmcnt(0)
	v_mfma_f32_32x32x16_bf16 v[80:95], v[220:223], v[236:239], v[80:95]
	v_cvt_pk_bf16_f32 v146, v141, v143
	v_cvt_pk_bf16_f32 v147, v140, v142
	v_cvt_pk_bf16_f32 v220, v132, v133
	v_cvt_pk_bf16_f32 v221, v134, v135
	v_cvt_pk_bf16_f32 v222, v124, v125
	v_cvt_pk_bf16_f32 v223, v126, v127
	v_permlane32_swap_b32_e32 v136, v138
	v_mfma_f32_32x32x16_bf16 v[64:79], v[232:235], v[236:239], v[64:79]
	v_mov_b32_e32 v233, v231
	v_cvt_pk_bf16_f32 v234, v128, v129
	v_cvt_pk_bf16_f32 v235, v130, v131
	v_cvt_pk_bf16_f32 v236, v120, v121
	s_nop 1
	v_permlane32_swap_b32_e32 v231, v233
	v_cvt_pk_bf16_f32 v237, v122, v123
	v_permlane32_swap_b32_e32 v234, v236
	v_permlane32_swap_b32_e32 v137, v139
	v_permlane32_swap_b32_e32 v144, v146
	v_permlane32_swap_b32_e32 v145, v147
	v_permlane32_swap_b32_e32 v220, v222
	v_permlane32_swap_b32_e32 v221, v223
	v_permlane32_swap_b32_e32 v235, v237
	s_sub_i32 s4, s14, 64
	s_cmp_lt_u32 s16, 3
	s_cselect_b32 s4, s15, s4
	s_ashr_i32 s5, s4, 31
	s_lshl_b64 s[76:77], s[4:5], 11
	s_mul_hi_i32 s79, s4, s87
	s_mul_i32 s78, s4, s87
	v_lshl_add_u64 v[120:121], v[148:149], 0, s[76:77]
	v_lshl_add_u64 v[124:125], v[156:157], 0, s[76:77]
	v_lshl_add_u64 v[130:131], v[150:151], 0, s[78:79]
	v_lshl_add_u64 v[134:135], v[152:153], 0, s[78:79]
	v_lshl_add_u64 v[140:141], v[154:155], 0, s[78:79]
	global_load_dwordx4 v[120:123], v[120:121], off
	global_load_dwordx4 v[124:127], v[124:125], off
	global_load_dwordx4 v[128:131], v[130:131], off
	global_load_dwordx4 v[132:135], v[134:135], off
	global_load_dwordx4 v[140:143], v[140:141], off
	ds_read_b64_tr_b16 v[238:239], v172 offset:0
	ds_read_b64_tr_b16 v[240:241], v172 offset:0x800
	ds_read_b64_tr_b16 v[242:243], v172 offset:0x1000
	ds_read_b64_tr_b16 v[244:245], v172 offset:0x1800
	ds_read_b64_tr_b16 v[246:247], v172 offset:0x2000
	ds_read_b64_tr_b16 v[248:249], v172 offset:0x2800
	ds_read_b64_tr_b16 v[250:251], v172 offset:0x3000
	ds_read_b64_tr_b16 v[252:253], v172 offset:0x3800
	s_waitcnt lgkmcnt(0)
	s_nop 0
	v_mfma_f32_32x32x16_bf16 v[0:15], v[136:139], v[238:241], v[0:15]
	ds_read_b64_tr_b16 v[238:239], v172 offset:0x200
	ds_read_b64_tr_b16 v[240:241], v172 offset:0xa00
	v_mfma_f32_32x32x16_bf16 v[0:15], v[144:147], v[242:245], v[0:15]
	ds_read_b64_tr_b16 v[242:243], v172 offset:0x1200
	ds_read_b64_tr_b16 v[244:245], v172 offset:0x1a00
	v_mfma_f32_32x32x16_bf16 v[0:15], v[220:223], v[246:249], v[0:15]
	ds_read_b64_tr_b16 v[246:247], v172 offset:0x2200
	ds_read_b64_tr_b16 v[248:249], v172 offset:0x2a00
	v_mfma_f32_32x32x16_bf16 v[0:15], v[234:237], v[250:253], v[0:15]
	ds_read_b64_tr_b16 v[250:251], v172 offset:0x3200
	ds_read_b64_tr_b16 v[252:253], v172 offset:0x3a00
	s_waitcnt lgkmcnt(0)
	v_mfma_f32_32x32x16_bf16 v[32:47], v[136:139], v[238:241], v[32:47]
	ds_read_b64_tr_b16 v[238:239], v172 offset:0x400
	ds_read_b64_tr_b16 v[240:241], v172 offset:0xc00
	v_mfma_f32_32x32x16_bf16 v[32:47], v[144:147], v[242:245], v[32:47]
	ds_read_b64_tr_b16 v[242:243], v172 offset:0x1400
	ds_read_b64_tr_b16 v[244:245], v172 offset:0x1c00
	v_mfma_f32_32x32x16_bf16 v[32:47], v[220:223], v[246:249], v[32:47]
	ds_read_b64_tr_b16 v[246:247], v172 offset:0x2400
	ds_read_b64_tr_b16 v[248:249], v172 offset:0x2c00
	v_mfma_f32_32x32x16_bf16 v[32:47], v[234:237], v[250:253], v[32:47]
	ds_read_b64_tr_b16 v[250:251], v172 offset:0x3400
	ds_read_b64_tr_b16 v[252:253], v172 offset:0x3c00
	s_waitcnt lgkmcnt(0)
	v_mfma_f32_32x32x16_bf16 v[16:31], v[136:139], v[238:241], v[16:31]
	ds_read_b64_tr_b16 v[238:239], v172 offset:0x600
	ds_read_b64_tr_b16 v[240:241], v172 offset:0xe00
	v_mfma_f32_32x32x16_bf16 v[16:31], v[144:147], v[242:245], v[16:31]
	ds_read_b64_tr_b16 v[242:243], v172 offset:0x1600
	ds_read_b64_tr_b16 v[244:245], v172 offset:0x1e00
	v_mfma_f32_32x32x16_bf16 v[16:31], v[220:223], v[246:249], v[16:31]
	ds_read_b64_tr_b16 v[246:247], v172 offset:0x2600
	ds_read_b64_tr_b16 v[248:249], v172 offset:0x2e00
	v_mfma_f32_32x32x16_bf16 v[16:31], v[234:237], v[250:253], v[16:31]
	ds_read_b64_tr_b16 v[250:251], v172 offset:0x3600
	ds_read_b64_tr_b16 v[252:253], v172 offset:0x3e00
	s_waitcnt lgkmcnt(0)
	v_mfma_f32_32x32x16_bf16 v[48:63], v[136:139], v[238:241], v[48:63]
	v_max_f32_e32 v136, v81, v81
	v_max_f32_e32 v137, v80, v80
	v_max_f32_e32 v136, v137, v136
	v_max3_f32 v136, v136, v82, v83
	v_max3_f32 v136, v136, v84, v85
	v_max3_f32 v136, v136, v86, v87
	v_max3_f32 v136, v136, v88, v89
	v_max3_f32 v136, v136, v90, v91
	v_mfma_f32_32x32x16_bf16 v[48:63], v[144:147], v[242:245], v[48:63]
	v_max3_f32 v136, v136, v92, v93
	v_max3_f32 v136, v136, v94, v95
	v_max3_f32 v136, v136, v64, v65
	v_max3_f32 v136, v136, v66, v67
	v_max3_f32 v136, v136, v68, v69
	v_max3_f32 v136, v136, v70, v71
	v_max3_f32 v136, v136, v72, v73
	v_max3_f32 v136, v136, v74, v75
	v_mfma_f32_32x32x16_bf16 v[48:63], v[220:223], v[246:249], v[48:63]
	v_max3_f32 v136, v136, v76, v77
	v_max3_f32 v136, v136, v78, v79
	v_mov_b32_e32 v137, v136
	s_nop 1
	v_permlane32_swap_b32_e32 v136, v137
	v_max_f32_e32 v136, v136, v137
	v_sub_f32_e32 v137, v136, v158
	v_cmp_ge_f32_e32 vcc, s90, v137
	v_max_f32_e32 v137, v158, v158
	v_mfma_f32_32x32x16_bf16 v[48:63], v[234:237], v[250:253], v[48:63]
	v_max_f32_e32 v136, v137, v136
	v_sub_f32_e32 v137, v158, v136
	v_exp_f32_e32 v137, v137
	s_cmp_eq_u64 vcc, exec
	s_cselect_b64 s[4:5], -1, 0
	s_barrier
	s_waitcnt vmcnt(0)
	v_cndmask_b32_e64 v234, v137, 1.0, s[4:5]
	v_cmp_gt_f32_e32 vcc, 1.0, v234
	ds_write_b128 v182, v[120:123]
	ds_write_b128 v183, v[124:127]
	ds_write_b128 v184, v[128:131] offset:32768
	ds_write_b128 v185, v[132:135] offset:32768
	s_waitcnt vmcnt(0)
	ds_write_b128 v186, v[140:143] offset:32768
	s_cbranch_vccz .LBB0_567
	s_and_saveexec_b64 s[6:7], s[2:3]
	ds_write_b32 v173, v234 offset:128
	s_or_b64 exec, exec, s[6:7]
	s_waitcnt lgkmcnt(0)
	v_add_u32_e32 v132, v169, v176
	ds_read_b128 v[120:123], v132 offset:224
	ds_read_b128 v[124:127], v132 offset:192
	ds_read_b128 v[128:131], v132 offset:160
	ds_read_b128 v[132:135], v132 offset:128
	s_waitcnt lgkmcnt(3)
	v_pk_mul_f32 v[12:13], v[12:13], v[120:121]
	s_waitcnt lgkmcnt(2)
	v_pk_mul_f32 v[8:9], v[8:9], v[124:125]
	s_waitcnt lgkmcnt(1)
	v_pk_mul_f32 v[4:5], v[4:5], v[128:129]
	v_pk_mul_f32 v[14:15], v[14:15], v[122:123]
	v_pk_mul_f32 v[10:11], v[10:11], v[126:127]
	v_pk_mul_f32 v[6:7], v[6:7], v[130:131]
	s_waitcnt lgkmcnt(0)
	v_pk_mul_f32 v[2:3], v[2:3], v[134:135]
	v_pk_mul_f32 v[0:1], v[0:1], v[132:133]
	v_pk_mul_f32 v[44:45], v[44:45], v[120:121]
	v_pk_mul_f32 v[40:41], v[40:41], v[124:125]
	v_pk_mul_f32 v[36:37], v[36:37], v[128:129]
	v_pk_mul_f32 v[46:47], v[46:47], v[122:123]
	v_pk_mul_f32 v[42:43], v[42:43], v[126:127]
	v_pk_mul_f32 v[38:39], v[38:39], v[130:131]
	v_pk_mul_f32 v[34:35], v[34:35], v[134:135]
	v_pk_mul_f32 v[32:33], v[32:33], v[132:133]
	v_pk_mul_f32 v[28:29], v[28:29], v[120:121]
	v_pk_mul_f32 v[24:25], v[24:25], v[124:125]
	v_pk_mul_f32 v[20:21], v[20:21], v[128:129]
	v_pk_mul_f32 v[30:31], v[30:31], v[122:123]
	v_pk_mul_f32 v[26:27], v[26:27], v[126:127]
	v_pk_mul_f32 v[22:23], v[22:23], v[130:131]
	v_pk_mul_f32 v[18:19], v[18:19], v[134:135]
	v_pk_mul_f32 v[16:17], v[16:17], v[132:133]
	v_pk_mul_f32 v[60:61], v[60:61], v[120:121]
	v_pk_mul_f32 v[56:57], v[56:57], v[124:125]
	v_pk_mul_f32 v[52:53], v[52:53], v[128:129]
	v_pk_mul_f32 v[62:63], v[62:63], v[122:123]
	v_pk_mul_f32 v[58:59], v[58:59], v[126:127]
	v_pk_mul_f32 v[54:55], v[54:55], v[130:131]
	v_pk_mul_f32 v[50:51], v[50:51], v[134:135]
	v_pk_mul_f32 v[48:49], v[48:49], v[132:133]
.LBB0_567:
	v_cndmask_b32_e64 v158, v136, v158, s[4:5]
	v_sub_f32_e32 v80, v80, v158
	v_sub_f32_e32 v81, v81, v158
	v_sub_f32_e32 v82, v82, v158
	v_sub_f32_e32 v83, v83, v158
	v_sub_f32_e32 v84, v84, v158
	v_sub_f32_e32 v85, v85, v158
	v_sub_f32_e32 v86, v86, v158
	v_sub_f32_e32 v87, v87, v158
	v_sub_f32_e32 v88, v88, v158
	v_sub_f32_e32 v89, v89, v158
	v_sub_f32_e32 v90, v90, v158
	v_sub_f32_e32 v91, v91, v158
	v_sub_f32_e32 v92, v92, v158
	v_sub_f32_e32 v93, v93, v158
	v_sub_f32_e32 v94, v94, v158
	v_sub_f32_e32 v95, v95, v158
	v_sub_f32_e32 v232, v76, v158
	v_sub_f32_e32 v235, v77, v158
	v_sub_f32_e32 v236, v78, v158
	v_exp_f32_e32 v133, v80
	v_exp_f32_e32 v135, v81
	v_exp_f32_e32 v131, v82
	v_exp_f32_e32 v134, v83
	v_exp_f32_e32 v130, v84
	v_exp_f32_e32 v132, v85
	v_exp_f32_e32 v128, v86
	v_exp_f32_e32 v129, v87
	v_exp_f32_e32 v125, v88
	v_exp_f32_e32 v127, v89
	v_exp_f32_e32 v124, v90
	v_exp_f32_e32 v126, v91
	v_exp_f32_e32 v121, v92
	v_exp_f32_e32 v123, v93
	v_exp_f32_e32 v120, v94
	v_exp_f32_e32 v122, v95
	v_sub_f32_e32 v178, v64, v158
	v_sub_f32_e32 v179, v65, v158
	v_sub_f32_e32 v213, v66, v158
	v_sub_f32_e32 v220, v67, v158
	v_sub_f32_e32 v221, v68, v158
	v_sub_f32_e32 v222, v69, v158
	v_sub_f32_e32 v223, v70, v158
	v_sub_f32_e32 v226, v71, v158
	v_sub_f32_e32 v227, v72, v158
	v_sub_f32_e32 v228, v73, v158
	v_sub_f32_e32 v229, v74, v158
	v_sub_f32_e32 v230, v75, v158
	v_sub_f32_e32 v237, v79, v158
	s_waitcnt lgkmcnt(0)
	s_barrier
	ds_read_b128 v[64:67], v187 offset:32768
	ds_read_b128 v[68:71], v187 offset:45056
	ds_read_b128 v[136:139], v189 offset:32768
	ds_read_b128 v[140:143], v189 offset:45056
	v_exp_f32_e32 v241, v236
	v_exp_f32_e32 v237, v237
	s_waitcnt lgkmcnt(3)
	v_mfma_f32_32x32x16_bf16 v[80:95], v[64:67], v[96:99], 0
	s_waitcnt lgkmcnt(2)
	v_mfma_f32_32x32x16_bf16 v[64:79], v[68:71], v[96:99], 0
	s_waitcnt lgkmcnt(1)
	v_mfma_f32_32x32x16_bf16 v[80:95], v[136:139], v[100:103], v[80:95]
	s_waitcnt lgkmcnt(0)
	v_mfma_f32_32x32x16_bf16 v[64:79], v[140:143], v[100:103], v[64:79]
	ds_read_b128 v[136:139], v190 offset:32768
	ds_read_b128 v[140:143], v190 offset:45056
	s_waitcnt lgkmcnt(1)
	v_mfma_f32_32x32x16_bf16 v[80:95], v[136:139], v[104:107], v[80:95]
	s_waitcnt lgkmcnt(0)
	v_mfma_f32_32x32x16_bf16 v[64:79], v[140:143], v[104:107], v[64:79]
	ds_read_b128 v[136:139], v191 offset:32768
	ds_read_b128 v[140:143], v191 offset:45056
	s_waitcnt lgkmcnt(1)
	v_mfma_f32_32x32x16_bf16 v[80:95], v[136:139], v[108:111], v[80:95]
	s_waitcnt lgkmcnt(0)
	v_mfma_f32_32x32x16_bf16 v[64:79], v[140:143], v[108:111], v[64:79]
	ds_read_b128 v[136:139], v192 offset:32768
	ds_read_b128 v[140:143], v192 offset:45056
	s_waitcnt lgkmcnt(1)
	v_mfma_f32_32x32x16_bf16 v[80:95], v[136:139], v[112:115], v[80:95]
	s_waitcnt lgkmcnt(0)
	v_mfma_f32_32x32x16_bf16 v[64:79], v[140:143], v[112:115], v[64:79]
	ds_read_b128 v[136:139], v193 offset:32768
	ds_read_b128 v[140:143], v193 offset:45056
	s_waitcnt lgkmcnt(1)
	v_mfma_f32_32x32x16_bf16 v[80:95], v[136:139], v[116:119], v[80:95]
	s_waitcnt lgkmcnt(0)
	v_mfma_f32_32x32x16_bf16 v[64:79], v[140:143], v[116:119], v[64:79]
	ds_read_b128 v[136:139], v194 offset:32768
	ds_read_b128 v[140:143], v194 offset:45056
	ds_read_b128 v[144:147], v171
	s_waitcnt lgkmcnt(0)
	v_mfma_f32_32x32x16_bf16 v[80:95], v[136:139], v[144:147], v[80:95]
	v_mfma_f32_32x32x16_bf16 v[64:79], v[140:143], v[144:147], v[64:79]
	ds_read_b128 v[136:139], v195 offset:32768
	ds_read_b128 v[140:143], v195 offset:45056
	ds_read_b128 v[144:147], v171 offset:1024
	s_waitcnt lgkmcnt(0)
	v_mfma_f32_32x32x16_bf16 v[80:95], v[136:139], v[144:147], v[80:95]
	v_mfma_f32_32x32x16_bf16 v[64:79], v[140:143], v[144:147], v[64:79]
	ds_read_b128 v[136:139], v196 offset:32768
	ds_read_b128 v[140:143], v196 offset:45056
	ds_read_b128 v[144:147], v171 offset:2048
	s_waitcnt lgkmcnt(0)
	v_mfma_f32_32x32x16_bf16 v[80:95], v[136:139], v[144:147], v[80:95]
	v_mfma_f32_32x32x16_bf16 v[64:79], v[140:143], v[144:147], v[64:79]
	ds_read_b128 v[136:139], v197 offset:32768
	ds_read_b128 v[140:143], v197 offset:45056
	ds_read_b128 v[144:147], v171 offset:3072
	s_waitcnt lgkmcnt(0)
	v_mfma_f32_32x32x16_bf16 v[80:95], v[136:139], v[144:147], v[80:95]
	v_mfma_f32_32x32x16_bf16 v[64:79], v[140:143], v[144:147], v[64:79]
	ds_read_b128 v[136:139], v199 offset:32768
	ds_read_b128 v[140:143], v199 offset:45056
	ds_read_b128 v[144:147], v171 offset:4096
	s_waitcnt lgkmcnt(0)
	v_mfma_f32_32x32x16_bf16 v[80:95], v[136:139], v[144:147], v[80:95]
	v_mfma_f32_32x32x16_bf16 v[64:79], v[140:143], v[144:147], v[64:79]
	ds_read_b128 v[136:139], v198 offset:32768
	ds_read_b128 v[140:143], v198 offset:45056
	ds_read_b128 v[144:147], v171 offset:5120
	s_waitcnt lgkmcnt(0)
	v_mfma_f32_32x32x16_bf16 v[80:95], v[136:139], v[144:147], v[80:95]
	v_add_f32_e32 v136, 0, v133
	v_add_f32_e32 v136, v135, v136
	v_add_f32_e32 v136, v131, v136
	v_add_f32_e32 v136, v134, v136
	v_add_f32_e32 v136, v130, v136
	v_add_f32_e32 v136, v132, v136
	v_add_f32_e32 v136, v128, v136
	v_add_f32_e32 v136, v129, v136
	v_add_f32_e32 v136, v125, v136
	v_add_f32_e32 v136, v127, v136
	v_add_f32_e32 v136, v124, v136
	v_add_f32_e32 v136, v126, v136
	v_mfma_f32_32x32x16_bf16 v[64:79], v[140:143], v[144:147], v[64:79]
	v_exp_f32_e32 v140, v178
	v_add_f32_e32 v136, v121, v136
	v_exp_f32_e32 v141, v179
	v_add_f32_e32 v136, v123, v136
	v_exp_f32_e32 v142, v213
	v_add_f32_e32 v136, v120, v136
	v_exp_f32_e32 v143, v220
	v_add_f32_e32 v136, v122, v136
	v_exp_f32_e32 v178, v221
	v_add_f32_e32 v136, v140, v136
	v_exp_f32_e32 v179, v222
	v_add_f32_e32 v136, v141, v136
	v_exp_f32_e32 v213, v223
	v_add_f32_e32 v136, v142, v136
	v_exp_f32_e32 v223, v226
	v_add_f32_e32 v136, v143, v136
	v_exp_f32_e32 v226, v227
	v_add_f32_e32 v136, v178, v136
	v_exp_f32_e32 v227, v228
	v_add_f32_e32 v136, v179, v136
	v_exp_f32_e32 v228, v229
	v_add_f32_e32 v136, v213, v136
	v_exp_f32_e32 v229, v230
	v_add_f32_e32 v136, v223, v136
	v_exp_f32_e32 v230, v232
	v_add_f32_e32 v136, v226, v136
	v_exp_f32_e32 v232, v235
	v_add_f32_e32 v136, v227, v136
	v_add_f32_e32 v136, v228, v136
	v_add_f32_e32 v136, v229, v136
	v_add_f32_e32 v136, v230, v136
	v_add_f32_e32 v136, v232, v136
	v_add_f32_e32 v136, v241, v136
	v_add_f32_e32 v235, v237, v136
	v_mov_b32_e32 v236, v235
	v_cvt_pk_bf16_f32 v136, v133, v135
	v_cvt_pk_bf16_f32 v137, v131, v134
	v_cvt_pk_bf16_f32 v138, v130, v132
	s_nop 1
	v_permlane32_swap_b32_e32 v235, v236
	v_cvt_pk_bf16_f32 v139, v128, v129
	v_permlane32_swap_b32_e32 v136, v138
	v_cvt_pk_bf16_f32 v144, v125, v127
	v_cvt_pk_bf16_f32 v145, v124, v126
	v_cvt_pk_bf16_f32 v146, v121, v123
	v_cvt_pk_bf16_f32 v147, v120, v122
	v_cvt_pk_bf16_f32 v220, v140, v141
	v_cvt_pk_bf16_f32 v221, v142, v143
	v_cvt_pk_bf16_f32 v222, v178, v179
	v_cvt_pk_bf16_f32 v223, v213, v223
	v_cvt_pk_bf16_f32 v238, v226, v227
	v_cvt_pk_bf16_f32 v239, v228, v229
	v_cvt_pk_bf16_f32 v240, v230, v232
	v_cvt_pk_bf16_f32 v241, v241, v237
	v_permlane32_swap_b32_e32 v137, v139
	v_permlane32_swap_b32_e32 v144, v146
	v_permlane32_swap_b32_e32 v145, v147
	v_permlane32_swap_b32_e32 v220, v222
	v_permlane32_swap_b32_e32 v221, v223
	v_permlane32_swap_b32_e32 v238, v240
	v_permlane32_swap_b32_e32 v239, v241
	s_add_i32 s4, s15, 64
	s_cmp_lt_u32 s16, 2
	s_cselect_b32 s4, s4, s14
	s_ashr_i32 s5, s4, 31
	s_lshl_b64 s[76:77], s[4:5], 11
	s_mul_hi_i32 s79, s4, s87
	s_mul_i32 s78, s4, s87
	v_lshl_add_u64 v[120:121], v[148:149], 0, s[76:77]
	v_lshl_add_u64 v[124:125], v[156:157], 0, s[76:77]
	v_lshl_add_u64 v[130:131], v[150:151], 0, s[78:79]
	v_lshl_add_u64 v[134:135], v[152:153], 0, s[78:79]
	v_lshl_add_u64 v[140:141], v[154:155], 0, s[78:79]
	global_load_dwordx4 v[120:123], v[120:121], off
	global_load_dwordx4 v[124:127], v[124:125], off
	global_load_dwordx4 v[128:131], v[130:131], off
	global_load_dwordx4 v[132:135], v[134:135], off
	global_load_dwordx4 v[140:143], v[140:141], off
	ds_read_b64_tr_b16 v[242:243], v175 offset:0
	ds_read_b64_tr_b16 v[244:245], v175 offset:0x800
	ds_read_b64_tr_b16 v[246:247], v175 offset:0x1000
	ds_read_b64_tr_b16 v[248:249], v175 offset:0x1800
	ds_read_b64_tr_b16 v[250:251], v175 offset:0x2000
	ds_read_b64_tr_b16 v[252:253], v175 offset:0x2800
	ds_read_b64_tr_b16 v[226:227], v175 offset:0x3000
	ds_read_b64_tr_b16 v[228:229], v175 offset:0x3800
	s_waitcnt lgkmcnt(0)
	s_nop 0
	v_mfma_f32_32x32x16_bf16 v[0:15], v[136:139], v[242:245], v[0:15]
	v_mfma_f32_32x32x16_bf16 v[0:15], v[144:147], v[246:249], v[0:15]
	v_mfma_f32_32x32x16_bf16 v[0:15], v[220:223], v[250:253], v[0:15]
	v_mfma_f32_32x32x16_bf16 v[0:15], v[238:241], v[226:229], v[0:15]
	ds_read_b64_tr_b16 v[226:227], v175 offset:0x200
	ds_read_b64_tr_b16 v[228:229], v175 offset:0xa00
	ds_read_b64_tr_b16 v[242:243], v175 offset:0x1200
	ds_read_b64_tr_b16 v[244:245], v175 offset:0x1a00
	ds_read_b64_tr_b16 v[246:247], v175 offset:0x2200
	ds_read_b64_tr_b16 v[248:249], v175 offset:0x2a00
	ds_read_b64_tr_b16 v[250:251], v175 offset:0x3200
	ds_read_b64_tr_b16 v[252:253], v175 offset:0x3a00
	s_waitcnt lgkmcnt(0)
	s_nop 0
	v_mfma_f32_32x32x16_bf16 v[32:47], v[136:139], v[226:229], v[32:47]
	ds_read_b64_tr_b16 v[226:227], v175 offset:0x400
	ds_read_b64_tr_b16 v[228:229], v175 offset:0xc00
	v_mfma_f32_32x32x16_bf16 v[32:47], v[144:147], v[242:245], v[32:47]
	ds_read_b64_tr_b16 v[242:243], v175 offset:0x1400
	ds_read_b64_tr_b16 v[244:245], v175 offset:0x1c00
	v_mfma_f32_32x32x16_bf16 v[32:47], v[220:223], v[246:249], v[32:47]
	ds_read_b64_tr_b16 v[246:247], v175 offset:0x2400
	ds_read_b64_tr_b16 v[248:249], v175 offset:0x2c00
	v_mfma_f32_32x32x16_bf16 v[32:47], v[238:241], v[250:253], v[32:47]
	ds_read_b64_tr_b16 v[250:251], v175 offset:0x3400
	ds_read_b64_tr_b16 v[252:253], v175 offset:0x3c00
	s_waitcnt lgkmcnt(0)
	v_mfma_f32_32x32x16_bf16 v[16:31], v[136:139], v[226:229], v[16:31]
	ds_read_b64_tr_b16 v[226:227], v175 offset:0x600
	ds_read_b64_tr_b16 v[228:229], v175 offset:0xe00
	v_mfma_f32_32x32x16_bf16 v[16:31], v[144:147], v[242:245], v[16:31]
	ds_read_b64_tr_b16 v[242:243], v175 offset:0x1600
	ds_read_b64_tr_b16 v[244:245], v175 offset:0x1e00
	v_mfma_f32_32x32x16_bf16 v[16:31], v[220:223], v[246:249], v[16:31]
	ds_read_b64_tr_b16 v[246:247], v175 offset:0x2600
	ds_read_b64_tr_b16 v[248:249], v175 offset:0x2e00
	v_mfma_f32_32x32x16_bf16 v[16:31], v[238:241], v[250:253], v[16:31]
	ds_read_b64_tr_b16 v[250:251], v175 offset:0x3600
	ds_read_b64_tr_b16 v[252:253], v175 offset:0x3e00
	s_waitcnt lgkmcnt(0)
	v_mfma_f32_32x32x16_bf16 v[48:63], v[136:139], v[226:229], v[48:63]
	v_max_f32_e32 v136, v81, v81
	v_max_f32_e32 v137, v80, v80
	v_max_f32_e32 v136, v137, v136
	v_max3_f32 v136, v136, v82, v83
	v_max3_f32 v136, v136, v84, v85
	v_max3_f32 v136, v136, v86, v87
	v_max3_f32 v136, v136, v88, v89
	v_max3_f32 v136, v136, v90, v91
	v_mfma_f32_32x32x16_bf16 v[48:63], v[144:147], v[242:245], v[48:63]
	v_max3_f32 v136, v136, v92, v93
	v_max3_f32 v136, v136, v94, v95
	v_max3_f32 v136, v136, v64, v65
	v_max3_f32 v136, v136, v66, v67
	v_max3_f32 v136, v136, v68, v69
	v_max3_f32 v136, v136, v70, v71
	v_max3_f32 v136, v136, v72, v73
	v_max3_f32 v136, v136, v74, v75
	v_mfma_f32_32x32x16_bf16 v[48:63], v[220:223], v[246:249], v[48:63]
	v_max3_f32 v136, v136, v76, v77
	v_max3_f32 v136, v136, v78, v79
	v_mov_b32_e32 v137, v136
	s_nop 1
	v_permlane32_swap_b32_e32 v136, v137
	v_max_f32_e32 v136, v136, v137
	v_sub_f32_e32 v137, v136, v158
	v_cmp_ge_f32_e32 vcc, s90, v137
	v_max_f32_e32 v137, v158, v158
	v_mfma_f32_32x32x16_bf16 v[48:63], v[238:241], v[250:253], v[48:63]
	v_max_f32_e32 v136, v137, v136
	v_sub_f32_e32 v137, v158, v136
	v_exp_f32_e32 v137, v137
	s_cmp_eq_u64 vcc, exec
	s_cselect_b64 s[4:5], -1, 0
	s_barrier
	s_waitcnt vmcnt(0)
	v_cndmask_b32_e64 v232, v137, 1.0, s[4:5]
	v_cmp_gt_f32_e32 vcc, 1.0, v232
	ds_write_b128 v182, v[120:123] offset:16384
	ds_write_b128 v183, v[124:127] offset:16384
	ds_write_b128 v184, v[128:131] offset:57344
	ds_write_b128 v185, v[132:135] offset:57344
	s_waitcnt vmcnt(0)
	ds_write_b128 v186, v[140:143] offset:57344
	s_cbranch_vccz .LBB0_571
	s_and_saveexec_b64 s[6:7], s[2:3]
	ds_write_b32 v173, v232 offset:128
	s_or_b64 exec, exec, s[6:7]
	s_waitcnt lgkmcnt(0)
	v_add_u32_e32 v132, v169, v176
	ds_read_b128 v[120:123], v132 offset:224
	ds_read_b128 v[124:127], v132 offset:192
	ds_read_b128 v[128:131], v132 offset:160
	ds_read_b128 v[132:135], v132 offset:128
	s_waitcnt lgkmcnt(3)
	v_pk_mul_f32 v[12:13], v[12:13], v[120:121]
	s_waitcnt lgkmcnt(2)
	v_pk_mul_f32 v[8:9], v[8:9], v[124:125]
	s_waitcnt lgkmcnt(1)
	v_pk_mul_f32 v[4:5], v[4:5], v[128:129]
	v_pk_mul_f32 v[14:15], v[14:15], v[122:123]
	v_pk_mul_f32 v[10:11], v[10:11], v[126:127]
	v_pk_mul_f32 v[6:7], v[6:7], v[130:131]
	s_waitcnt lgkmcnt(0)
	v_pk_mul_f32 v[2:3], v[2:3], v[134:135]
	v_pk_mul_f32 v[0:1], v[0:1], v[132:133]
	v_pk_mul_f32 v[44:45], v[44:45], v[120:121]
	v_pk_mul_f32 v[40:41], v[40:41], v[124:125]
	v_pk_mul_f32 v[36:37], v[36:37], v[128:129]
	v_pk_mul_f32 v[46:47], v[46:47], v[122:123]
	v_pk_mul_f32 v[42:43], v[42:43], v[126:127]
	v_pk_mul_f32 v[38:39], v[38:39], v[130:131]
	v_pk_mul_f32 v[34:35], v[34:35], v[134:135]
	v_pk_mul_f32 v[32:33], v[32:33], v[132:133]
	v_pk_mul_f32 v[28:29], v[28:29], v[120:121]
	v_pk_mul_f32 v[24:25], v[24:25], v[124:125]
	v_pk_mul_f32 v[20:21], v[20:21], v[128:129]
	v_pk_mul_f32 v[30:31], v[30:31], v[122:123]
	v_pk_mul_f32 v[26:27], v[26:27], v[126:127]
	v_pk_mul_f32 v[22:23], v[22:23], v[130:131]
	v_pk_mul_f32 v[18:19], v[18:19], v[134:135]
	v_pk_mul_f32 v[16:17], v[16:17], v[132:133]
	v_pk_mul_f32 v[60:61], v[60:61], v[120:121]
	v_pk_mul_f32 v[56:57], v[56:57], v[124:125]
	v_pk_mul_f32 v[52:53], v[52:53], v[128:129]
	v_pk_mul_f32 v[62:63], v[62:63], v[122:123]
	v_pk_mul_f32 v[58:59], v[58:59], v[126:127]
	v_pk_mul_f32 v[54:55], v[54:55], v[130:131]
	v_pk_mul_f32 v[50:51], v[50:51], v[134:135]
	v_pk_mul_f32 v[48:49], v[48:49], v[132:133]

.LBB0_573:
	ds_read_b128 v[64:67], v187 offset:57344
	ds_read_b128 v[68:71], v202 offset:57344
	s_waitcnt lgkmcnt(1)
	v_mfma_f32_32x32x16_bf16 v[80:95], v[64:67], v[96:99], 0
	s_waitcnt lgkmcnt(0)
	v_mfma_f32_32x32x16_bf16 v[64:79], v[68:71], v[96:99], 0
	ds_read_b128 v[96:99], v189 offset:57344
	ds_read_b128 v[148:151], v201 offset:57344
	s_waitcnt lgkmcnt(1)
	v_mfma_f32_32x32x16_bf16 v[80:95], v[96:99], v[100:103], v[80:95]
	s_waitcnt lgkmcnt(0)
	v_mfma_f32_32x32x16_bf16 v[64:79], v[148:151], v[100:103], v[64:79]
	ds_read_b128 v[96:99], v190 offset:57344
	ds_read_b128 v[100:103], v209 offset:57344
	s_waitcnt lgkmcnt(1)
	v_mfma_f32_32x32x16_bf16 v[80:95], v[96:99], v[104:107], v[80:95]
	s_waitcnt lgkmcnt(0)
	v_mfma_f32_32x32x16_bf16 v[64:79], v[100:103], v[104:107], v[64:79]
	ds_read_b128 v[96:99], v191 offset:57344
	ds_read_b128 v[100:103], v212 offset:57344
	s_waitcnt lgkmcnt(1)
	v_mfma_f32_32x32x16_bf16 v[80:95], v[96:99], v[108:111], v[80:95]
	s_waitcnt lgkmcnt(0)
	v_mfma_f32_32x32x16_bf16 v[64:79], v[100:103], v[108:111], v[64:79]
	ds_read_b128 v[96:99], v192 offset:57344
	ds_read_b128 v[100:103], v211 offset:57344
	v_exp_f32_e32 v108, v134
	v_exp_f32_e32 v109, v135
	v_exp_f32_e32 v110, v124
	v_exp_f32_e32 v111, v125
	s_waitcnt lgkmcnt(1)
	v_mfma_f32_32x32x16_bf16 v[80:95], v[96:99], v[112:115], v[80:95]
	s_waitcnt lgkmcnt(0)
	v_mfma_f32_32x32x16_bf16 v[64:79], v[100:103], v[112:115], v[64:79]
	ds_read_b128 v[96:99], v193 offset:57344
	ds_read_b128 v[100:103], v210 offset:57344
	v_exp_f32_e32 v112, v126
	v_exp_f32_e32 v113, v127
	v_exp_f32_e32 v114, v128
	v_exp_f32_e32 v115, v129
	s_waitcnt lgkmcnt(1)
	v_mfma_f32_32x32x16_bf16 v[80:95], v[96:99], v[116:119], v[80:95]
	s_waitcnt lgkmcnt(0)
	v_mfma_f32_32x32x16_bf16 v[64:79], v[100:103], v[116:119], v[64:79]
	ds_read_b128 v[96:99], v194 offset:57344
	ds_read_b128 v[100:103], v208 offset:57344
	ds_read_b128 v[104:107], v171
	v_exp_f32_e32 v116, v130
	v_exp_f32_e32 v117, v131
	v_exp_f32_e32 v118, v120
	v_exp_f32_e32 v119, v121
	v_exp_f32_e32 v120, v122
	v_exp_f32_e32 v121, v123
	s_waitcnt lgkmcnt(0)
	v_mfma_f32_32x32x16_bf16 v[80:95], v[96:99], v[104:107], v[80:95]
	v_mfma_f32_32x32x16_bf16 v[64:79], v[100:103], v[104:107], v[64:79]
	ds_read_b128 v[96:99], v195 offset:57344
	ds_read_b128 v[100:103], v207 offset:57344
	ds_read_b128 v[104:107], v171 offset:1024
	s_waitcnt lgkmcnt(0)
	v_mfma_f32_32x32x16_bf16 v[80:95], v[96:99], v[104:107], v[80:95]
	v_mfma_f32_32x32x16_bf16 v[64:79], v[100:103], v[104:107], v[64:79]
	ds_read_b128 v[96:99], v196 offset:57344
	ds_read_b128 v[100:103], v206 offset:57344
	ds_read_b128 v[104:107], v171 offset:2048
	s_waitcnt lgkmcnt(0)
	v_mfma_f32_32x32x16_bf16 v[80:95], v[96:99], v[104:107], v[80:95]
	v_mfma_f32_32x32x16_bf16 v[64:79], v[100:103], v[104:107], v[64:79]
	ds_read_b128 v[96:99], v197 offset:57344
	ds_read_b128 v[100:103], v205 offset:57344
	ds_read_b128 v[104:107], v171 offset:3072
	s_waitcnt lgkmcnt(0)
	v_mfma_f32_32x32x16_bf16 v[80:95], v[96:99], v[104:107], v[80:95]
	v_mfma_f32_32x32x16_bf16 v[64:79], v[100:103], v[104:107], v[64:79]
	ds_read_b128 v[96:99], v199 offset:57344
	ds_read_b128 v[100:103], v204 offset:57344
	ds_read_b128 v[104:107], v171 offset:4096
	s_waitcnt lgkmcnt(0)
	v_mfma_f32_32x32x16_bf16 v[80:95], v[96:99], v[104:107], v[80:95]
	v_mfma_f32_32x32x16_bf16 v[64:79], v[100:103], v[104:107], v[64:79]
	ds_read_b128 v[96:99], v198 offset:57344
	ds_read_b128 v[100:103], v203 offset:57344
	ds_read_b128 v[104:107], v171 offset:5120
	s_waitcnt lgkmcnt(0)
	v_mfma_f32_32x32x16_bf16 v[80:95], v[96:99], v[104:107], v[80:95]
	v_add_f32_e32 v96, 0, v136
	v_add_f32_e32 v96, v230, v96
	v_add_f32_e32 v96, v137, v96
	v_add_f32_e32 v96, v229, v96
	v_add_f32_e32 v96, v138, v96
	v_add_f32_e32 v96, v228, v96
	v_add_f32_e32 v96, v139, v96
	v_add_f32_e32 v96, v213, v96
	v_add_f32_e32 v96, v144, v96
	v_add_f32_e32 v96, v147, v96
	v_add_f32_e32 v96, v145, v96
	v_add_f32_e32 v96, v146, v96
	v_mfma_f32_32x32x16_bf16 v[64:79], v[100:103], v[104:107], v[64:79]
	v_exp_f32_e32 v106, v132
	v_add_f32_e32 v96, v141, v96
	v_exp_f32_e32 v107, v133
	v_add_f32_e32 v96, v143, v96
	v_add_f32_e32 v96, v140, v96
	v_add_f32_e32 v96, v142, v96
	v_add_f32_e32 v96, v106, v96
	v_add_f32_e32 v96, v107, v96
	v_add_f32_e32 v96, v108, v96
	v_add_f32_e32 v96, v109, v96
	v_add_f32_e32 v96, v110, v96
	v_add_f32_e32 v96, v111, v96
	v_add_f32_e32 v96, v112, v96
	v_add_f32_e32 v96, v113, v96
	v_add_f32_e32 v96, v114, v96
	v_add_f32_e32 v96, v115, v96
	v_add_f32_e32 v96, v116, v96
	v_add_f32_e32 v96, v117, v96
	v_add_f32_e32 v96, v118, v96
	v_add_f32_e32 v96, v119, v96
	v_add_f32_e32 v96, v120, v96
	v_add_f32_e32 v96, v121, v96
	v_mov_b32_e32 v97, v96
	v_cvt_pk_bf16_f32 v98, v136, v230
	v_cvt_pk_bf16_f32 v99, v137, v229
	v_cvt_pk_bf16_f32 v100, v138, v228
	v_cvt_pk_bf16_f32 v101, v139, v213
	s_nop 1
	v_permlane32_swap_b32_e32 v96, v97
	v_permlane32_swap_b32_e32 v98, v100
	v_permlane32_swap_b32_e32 v99, v101
	v_cvt_pk_bf16_f32 v102, v144, v147
	v_cvt_pk_bf16_f32 v103, v145, v146
	v_cvt_pk_bf16_f32 v104, v141, v143
	v_cvt_pk_bf16_f32 v105, v140, v142
	v_cvt_pk_bf16_f32 v106, v106, v107
	v_cvt_pk_bf16_f32 v107, v108, v109
	v_cvt_pk_bf16_f32 v108, v110, v111
	v_cvt_pk_bf16_f32 v109, v112, v113
	v_cvt_pk_bf16_f32 v110, v114, v115
	v_cvt_pk_bf16_f32 v111, v116, v117
	v_cvt_pk_bf16_f32 v112, v118, v119
	v_cvt_pk_bf16_f32 v113, v120, v121
	s_nop 0
	v_permlane32_swap_b32_e32 v102, v104
	v_permlane32_swap_b32_e32 v103, v105
	v_permlane32_swap_b32_e32 v106, v108
	v_permlane32_swap_b32_e32 v107, v109
	v_permlane32_swap_b32_e32 v110, v112
	v_permlane32_swap_b32_e32 v111, v113
	ds_read_b64_tr_b16 v[114:115], v172 offset:0
	ds_read_b64_tr_b16 v[116:117], v172 offset:0x800
	ds_read_b64_tr_b16 v[118:119], v172 offset:0x1000
	ds_read_b64_tr_b16 v[120:121], v172 offset:0x1800
	ds_read_b64_tr_b16 v[122:123], v172 offset:0x2000
	ds_read_b64_tr_b16 v[124:125], v172 offset:0x2800
	ds_read_b64_tr_b16 v[126:127], v172 offset:0x3000
	ds_read_b64_tr_b16 v[128:129], v172 offset:0x3800
	s_waitcnt lgkmcnt(0)
	s_nop 0
	v_mfma_f32_32x32x16_bf16 v[0:15], v[98:101], v[114:117], v[0:15]
	ds_read_b64_tr_b16 v[114:115], v172 offset:0x200
	ds_read_b64_tr_b16 v[116:117], v172 offset:0xa00
	v_mfma_f32_32x32x16_bf16 v[0:15], v[102:105], v[118:121], v[0:15]
	ds_read_b64_tr_b16 v[118:119], v172 offset:0x1200
	ds_read_b64_tr_b16 v[120:121], v172 offset:0x1a00
	v_mfma_f32_32x32x16_bf16 v[0:15], v[106:109], v[122:125], v[0:15]
	ds_read_b64_tr_b16 v[122:123], v172 offset:0x2200
	ds_read_b64_tr_b16 v[124:125], v172 offset:0x2a00
	v_mfma_f32_32x32x16_bf16 v[0:15], v[110:113], v[126:129], v[0:15]
	ds_read_b64_tr_b16 v[126:127], v172 offset:0x3200
	ds_read_b64_tr_b16 v[128:129], v172 offset:0x3a00
	s_waitcnt lgkmcnt(0)
	v_mfma_f32_32x32x16_bf16 v[32:47], v[98:101], v[114:117], v[32:47]
	ds_read_b64_tr_b16 v[114:115], v172 offset:0x400
	ds_read_b64_tr_b16 v[116:117], v172 offset:0xc00
	v_mfma_f32_32x32x16_bf16 v[32:47], v[102:105], v[118:121], v[32:47]
	ds_read_b64_tr_b16 v[118:119], v172 offset:0x1400
	ds_read_b64_tr_b16 v[120:121], v172 offset:0x1c00
	v_mfma_f32_32x32x16_bf16 v[32:47], v[106:109], v[122:125], v[32:47]
	ds_read_b64_tr_b16 v[122:123], v172 offset:0x2400
	ds_read_b64_tr_b16 v[124:125], v172 offset:0x2c00
	v_mfma_f32_32x32x16_bf16 v[32:47], v[110:113], v[126:129], v[32:47]
	ds_read_b64_tr_b16 v[126:127], v172 offset:0x3400
	ds_read_b64_tr_b16 v[128:129], v172 offset:0x3c00
	s_waitcnt lgkmcnt(0)
	v_mfma_f32_32x32x16_bf16 v[16:31], v[98:101], v[114:117], v[16:31]
	ds_read_b64_tr_b16 v[114:115], v172 offset:0x600
	ds_read_b64_tr_b16 v[116:117], v172 offset:0xe00
	v_mfma_f32_32x32x16_bf16 v[16:31], v[102:105], v[118:121], v[16:31]
	ds_read_b64_tr_b16 v[118:119], v172 offset:0x1600
	ds_read_b64_tr_b16 v[120:121], v172 offset:0x1e00
	v_mfma_f32_32x32x16_bf16 v[16:31], v[106:109], v[122:125], v[16:31]
	ds_read_b64_tr_b16 v[122:123], v172 offset:0x2600
	ds_read_b64_tr_b16 v[124:125], v172 offset:0x2e00
	v_mfma_f32_32x32x16_bf16 v[16:31], v[110:113], v[126:129], v[16:31]
	ds_read_b64_tr_b16 v[126:127], v172 offset:0x3600
	ds_read_b64_tr_b16 v[128:129], v172 offset:0x3e00
	s_waitcnt lgkmcnt(0)
	v_mfma_f32_32x32x16_bf16 v[48:63], v[98:101], v[114:117], v[48:63]
	v_max_f32_e32 v98, v81, v81
	v_max_f32_e32 v99, v80, v80
	v_max_f32_e32 v98, v99, v98
	v_max3_f32 v98, v98, v82, v83
	v_max3_f32 v98, v98, v84, v85
	v_max3_f32 v98, v98, v86, v87
	v_max3_f32 v98, v98, v88, v89
	v_max3_f32 v98, v98, v90, v91
	v_mfma_f32_32x32x16_bf16 v[48:63], v[102:105], v[118:121], v[48:63]
	v_max3_f32 v98, v98, v92, v93
	v_max3_f32 v98, v98, v94, v95
	v_max3_f32 v98, v98, v64, v65
	v_max3_f32 v98, v98, v66, v67
	v_max3_f32 v98, v98, v68, v69
	v_max3_f32 v98, v98, v70, v71
	v_max3_f32 v98, v98, v72, v73
	v_max3_f32 v98, v98, v74, v75
	v_mfma_f32_32x32x16_bf16 v[48:63], v[106:109], v[122:125], v[48:63]
	v_max3_f32 v98, v98, v76, v77
	v_max3_f32 v98, v98, v78, v79
	v_mov_b32_e32 v99, v98
	s_nop 1
	v_permlane32_swap_b32_e32 v98, v99
	v_max_f32_e32 v98, v98, v99
	v_sub_f32_e32 v99, v98, v158
	v_cmp_ge_f32_e32 vcc, s90, v99
	v_max_f32_e32 v99, v158, v158
	v_mfma_f32_32x32x16_bf16 v[48:63], v[110:113], v[126:129], v[48:63]
	v_max_f32_e32 v99, v99, v98
	v_sub_f32_e32 v98, v158, v99
	v_exp_f32_e32 v98, v98
	s_cmp_eq_u64 vcc, exec
	s_cselect_b64 s[4:5], -1, 0
	v_cndmask_b32_e64 v98, v98, 1.0, s[4:5]
	v_cmp_gt_f32_e32 vcc, 1.0, v98
	s_barrier
	s_cbranch_vccz .LBB0_577
	s_and_saveexec_b64 s[6:7], s[2:3]
	ds_write_b32 v173, v98 offset:128
	s_or_b64 exec, exec, s[6:7]
	s_waitcnt lgkmcnt(0)
	v_add_u32_e32 v112, v169, v176
	ds_read_b128 v[100:103], v112 offset:224
	ds_read_b128 v[104:107], v112 offset:192
	ds_read_b128 v[108:111], v112 offset:160
	ds_read_b128 v[112:115], v112 offset:128
	s_waitcnt lgkmcnt(3)
	v_pk_mul_f32 v[12:13], v[12:13], v[100:101]
	s_waitcnt lgkmcnt(2)
	v_pk_mul_f32 v[8:9], v[8:9], v[104:105]
	s_waitcnt lgkmcnt(1)
	v_pk_mul_f32 v[4:5], v[4:5], v[108:109]
	v_pk_mul_f32 v[14:15], v[14:15], v[102:103]
	v_pk_mul_f32 v[10:11], v[10:11], v[106:107]
	v_pk_mul_f32 v[6:7], v[6:7], v[110:111]
	s_waitcnt lgkmcnt(0)
	v_pk_mul_f32 v[2:3], v[2:3], v[114:115]
	v_pk_mul_f32 v[0:1], v[0:1], v[112:113]
	v_pk_mul_f32 v[44:45], v[44:45], v[100:101]
	v_pk_mul_f32 v[40:41], v[40:41], v[104:105]
	v_pk_mul_f32 v[36:37], v[36:37], v[108:109]
	v_pk_mul_f32 v[46:47], v[46:47], v[102:103]
	v_pk_mul_f32 v[42:43], v[42:43], v[106:107]
	v_pk_mul_f32 v[38:39], v[38:39], v[110:111]
	v_pk_mul_f32 v[34:35], v[34:35], v[114:115]
	v_pk_mul_f32 v[32:33], v[32:33], v[112:113]
	v_pk_mul_f32 v[28:29], v[28:29], v[100:101]
	v_pk_mul_f32 v[24:25], v[24:25], v[104:105]
	v_pk_mul_f32 v[20:21], v[20:21], v[108:109]
	v_pk_mul_f32 v[30:31], v[30:31], v[102:103]
	v_pk_mul_f32 v[26:27], v[26:27], v[106:107]
	v_pk_mul_f32 v[22:23], v[22:23], v[110:111]
	v_pk_mul_f32 v[18:19], v[18:19], v[114:115]
	v_pk_mul_f32 v[16:17], v[16:17], v[112:113]
	v_pk_mul_f32 v[60:61], v[60:61], v[100:101]
	v_pk_mul_f32 v[56:57], v[56:57], v[104:105]
	v_pk_mul_f32 v[52:53], v[52:53], v[108:109]
	v_pk_mul_f32 v[62:63], v[62:63], v[102:103]
	v_pk_mul_f32 v[58:59], v[58:59], v[106:107]
	v_pk_mul_f32 v[54:55], v[54:55], v[110:111]
	v_pk_mul_f32 v[50:51], v[50:51], v[114:115]
	v_pk_mul_f32 v[48:49], v[48:49], v[112:113]
